# in-proj GEMM K-loop: LDS-DMA issue rebalanced to 4 per phase (SA00 restage B->C, SA10 restage D->next A), vmcnt recounted; plus sub4 epilogue batched loads
# speedup vs baseline: 1.0092x; 1.0076x over previous
; #define PG8_STAGE(bufoff, gbase, voff) do { _Pragma("unroll") for (int _i = 0; _i < 2; ++_i) \
;         __builtin_amdgcn_global_load_lds((const unsigned*)((const char*)(gbase) + (voff)[_i]), (LAS unsigned*)(lds + (bufoff) + ldsw + _i * 8192), 16, 0, 0); } while (0)
; #define PG8_LDA(dst, b, h) do { _Pragma("unroll") for (int m = 0; m < 4; ++m) _Pragma("unroll") for (int k = 0; k < 2; ++k) dst[m][k] = *(const LAS bf16x8*)(lds + PG8_SA(b, h) + aoff + m * 2048 + k * 1024); } while (0)
; #define PG8_LDB(dst, b, h) do { _Pragma("unroll") for (int n = 0; n < 2; ++n) _Pragma("unroll") for (int k = 0; k < 2; ++k) dst[n][k] = *(const LAS bf16x8*)(lds + PG8_SB(b, h) + boff + n * 2048 + k * 1024); } while (0)
; #define PG8_MMA(ai, bj, At, Bt) do { __builtin_amdgcn_s_setprio(1); _Pragma("unroll") for (int m = 0; m < 4; ++m) _Pragma("unroll") for (int n = 0; n < 2; ++n) _Pragma("unroll") for (int k = 0; k < 2; ++k) \
;         acc[ai][bj][m][n] = __builtin_amdgcn_mfma_f32_16x16x32_bf16(Bt[n][k], At[m][k], acc[ai][bj][m][n], 0, 0, 0); __builtin_amdgcn_s_setprio(0); } while (0)
; #define PG8_WAIT_V(n) asm volatile("s_waitcnt vmcnt(" #n ")" ::: "memory")
; #define PG8_WAIT_L(n) asm volatile("s_waitcnt lgkmcnt(" #n ")" ::: "memory")
; #define PG8_BAR __builtin_amdgcn_s_barrier()
; #define PG8_SCHED __builtin_amdgcn_sched_barrier(0)
; template <class Epi, bool ALIGN_EPI = true, class Sched = StaticOrder>
; __device__ __forceinline__ void gemm_phase(LAS unsigned char* lds, const Gemm g, const Sched& S, const Epi& E) {
;     ...
;             PG8_LDB(B0, 0, 0); PG8_LDB(B1, 0, 1); PG8_SCHED; PG8_LDA(At, 0, 0); PG8_STAGE(PG8_SA(1, 1), a1 + hstepA, voffA);
;             PG8_WAIT_V(8); PG8_WAIT_L(0); PG8_BAR; PG8_MMA(0, 0, At, B0); PG8_MMA(0, 1, At, B1); PG8_BAR; PG8_SCHED;
;             PG8_LDA(At, 0, 1); PG8_STAGE(PG8_SB(0, 0), b2, voffB); PG8_STAGE(PG8_SB(0, 1), b2 + hstepB, voffB); PG8_STAGE(PG8_SA(0, 0), a2, voffA);
;             PG8_WAIT_V(8); PG8_WAIT_L(0); PG8_BAR; PG8_MMA(1, 0, At, B0); PG8_MMA(1, 1, At, B1); PG8_BAR; PG8_SCHED;
.LBB0_374:
	s_add_u32 s36, s58, 0xfffc0080
	s_addc_u32 s37, s59, -1
	s_add_i32 s46, 0, 0x10000
	s_cmp_eq_u32 s45, 12
	s_cselect_b32 s37, s9, s37
	s_cselect_b32 s36, s12, s36
	s_cselect_b32 s61, s7, s44
	s_cselect_b32 s60, s13, s43
	s_add_i32 s48, 0, 0x14000
	v_add_u32_e32 v160, s46, v145
	v_add_u32_e32 v176, s48, v145
	ds_read_b128 v[140:143], v160
	ds_read_b128 v[152:155], v160 offset:1024
	ds_read_b128 v[156:159], v160 offset:2048
	ds_read_b128 v[160:163], v160 offset:3072
	ds_read_b128 v[164:167], v176
	ds_read_b128 v[168:171], v176 offset:1024
	ds_read_b128 v[172:175], v176 offset:2048
	ds_read_b128 v[176:179], v176 offset:3072
	s_add_u32 s100, s58, 0xfffc0000
	s_addc_u32 s101, s59, -1
	v_lshl_add_u64 v[196:197], s[100:101], 0, v[136:137]
	s_mov_b32 m0, s38
	v_lshl_add_u64 v[190:191], s[100:101], 0, v[138:139]
	global_load_lds_dwordx4 v[196:197], off
	s_mov_b32 m0, s39
	s_nop 0
	global_load_lds_dwordx4 v[190:191], off
	v_lshl_add_u64 v[188:189], s[58:59], 0, v[136:137]
	s_add_i32 m0, s11, 0xc000
	ds_read_b128 v[180:183], v151
	ds_read_b128 v[184:187], v151 offset:1024
	ds_read_b128 v[198:201], v151 offset:2048
	ds_read_b128 v[202:205], v151 offset:3072
	ds_read_b128 v[216:219], v151 offset:4096
	ds_read_b128 v[220:223], v151 offset:5120
	ds_read_b128 v[224:227], v151 offset:6144
	ds_read_b128 v[234:237], v151 offset:7168
	global_load_lds_dwordx4 v[188:189], off
	v_lshl_add_u64 v[188:189], s[58:59], 0, v[138:139]
	s_add_i32 m0, s11, 0xe000
	s_nop 0
	global_load_lds_dwordx4 v[188:189], off
	s_waitcnt vmcnt(8)
	s_waitcnt lgkmcnt(0)
	s_barrier
	s_setprio 1
	s_waitcnt lgkmcnt(0)
	v_mfma_f32_16x16x32_bf16 v[126:129], v[140:143], v[180:183], v[126:129]
	v_mfma_f32_16x16x32_bf16 v[122:125], v[156:159], v[180:183], v[122:125]
	v_mfma_f32_16x16x32_bf16 v[118:121], v[140:143], v[198:201], v[118:121]
	v_mfma_f32_16x16x32_bf16 v[110:113], v[156:159], v[198:201], v[110:113]
	v_mfma_f32_16x16x32_bf16 v[102:105], v[140:143], v[216:219], v[102:105]
	v_mfma_f32_16x16x32_bf16 v[94:97], v[156:159], v[216:219], v[94:97]
	v_mfma_f32_16x16x32_bf16 v[86:89], v[140:143], v[224:227], v[86:89]
	v_mfma_f32_16x16x32_bf16 v[78:81], v[156:159], v[224:227], v[78:81]
	v_mfma_f32_16x16x32_bf16 v[126:129], v[152:155], v[184:187], v[126:129]
	v_mfma_f32_16x16x32_bf16 v[122:125], v[160:163], v[184:187], v[122:125]
	v_mfma_f32_16x16x32_bf16 v[118:121], v[152:155], v[202:205], v[118:121]
	v_mfma_f32_16x16x32_bf16 v[110:113], v[160:163], v[202:205], v[110:113]
	v_mfma_f32_16x16x32_bf16 v[102:105], v[152:155], v[220:223], v[102:105]
	v_mfma_f32_16x16x32_bf16 v[94:97], v[160:163], v[220:223], v[94:97]
	v_mfma_f32_16x16x32_bf16 v[86:89], v[152:155], v[234:237], v[86:89]
	v_mfma_f32_16x16x32_bf16 v[78:81], v[160:163], v[234:237], v[78:81]
	s_setprio 0
	s_setprio 1
	v_mfma_f32_16x16x32_bf16 v[114:117], v[164:167], v[180:183], v[114:117]
	v_mfma_f32_16x16x32_bf16 v[106:109], v[172:175], v[180:183], v[106:109]
	v_mfma_f32_16x16x32_bf16 v[98:101], v[164:167], v[198:201], v[98:101]
	v_mfma_f32_16x16x32_bf16 v[90:93], v[172:175], v[198:201], v[90:93]
	v_mfma_f32_16x16x32_bf16 v[82:85], v[164:167], v[216:219], v[82:85]
	v_mfma_f32_16x16x32_bf16 v[74:77], v[172:175], v[216:219], v[74:77]
	v_mfma_f32_16x16x32_bf16 v[70:73], v[164:167], v[224:227], v[70:73]
	v_mfma_f32_16x16x32_bf16 v[66:69], v[172:175], v[224:227], v[66:69]
	v_mfma_f32_16x16x32_bf16 v[114:117], v[168:171], v[184:187], v[114:117]
	v_mfma_f32_16x16x32_bf16 v[106:109], v[176:179], v[184:187], v[106:109]
	v_mfma_f32_16x16x32_bf16 v[98:101], v[168:171], v[202:205], v[98:101]
	v_mfma_f32_16x16x32_bf16 v[90:93], v[176:179], v[202:205], v[90:93]
	v_mfma_f32_16x16x32_bf16 v[82:85], v[168:171], v[220:223], v[82:85]
	v_mfma_f32_16x16x32_bf16 v[74:77], v[176:179], v[220:223], v[74:77]
	v_mfma_f32_16x16x32_bf16 v[70:73], v[168:171], v[234:237], v[70:73]
	v_mfma_f32_16x16x32_bf16 v[66:69], v[176:179], v[234:237], v[66:69]
	s_setprio 0
	s_barrier
	s_add_i32 s46, s46, s19
	v_lshl_add_u64 v[188:189], s[60:61], 0, v[0:1]
	s_mov_b32 m0, s46
	ds_read_b128 v[180:183], v151 offset:16384
	ds_read_b128 v[184:187], v151 offset:17408
	ds_read_b128 v[198:201], v151 offset:18432
	ds_read_b128 v[202:205], v151 offset:19456
	ds_read_b128 v[216:219], v151 offset:20480
	ds_read_b128 v[220:223], v151 offset:21504
	ds_read_b128 v[224:227], v151 offset:22528
	ds_read_b128 v[234:237], v151 offset:23552
	global_load_lds_dwordx4 v[188:189], off
	s_add_i32 m0, s46, 0x2000
	s_add_u32 s46, s60, 0x40000
	v_lshl_add_u64 v[190:191], s[60:61], 0, v[134:135]
	s_addc_u32 s47, s61, 0
	s_add_i32 s48, s48, s19
	global_load_lds_dwordx4 v[190:191], off
	v_lshl_add_u64 v[192:193], s[46:47], 0, v[0:1]
	s_mov_b32 m0, s48
	v_lshl_add_u64 v[194:195], s[36:37], 0, v[132:133]
	global_load_lds_dwordx4 v[192:193], off
	v_lshl_add_u64 v[192:193], s[46:47], 0, v[134:135]
	s_add_i32 m0, s48, 0x2000
	s_nop 0
	global_load_lds_dwordx4 v[192:193], off
	v_lshl_add_u64 v[192:193], s[36:37], 0, v[130:131]
	s_waitcnt vmcnt(6)
	s_waitcnt lgkmcnt(0)
	s_barrier
; #define PG8_STAGE(bufoff, gbase, voff) do { _Pragma("unroll") for (int _i = 0; _i < 2; ++_i) \
;         __builtin_amdgcn_global_load_lds((const unsigned*)((const char*)(gbase) + (voff)[_i]), (LAS unsigned*)(lds + (bufoff) + ldsw + _i * 8192), 16, 0, 0); } while (0)
; #define PG8_LDA(dst, b, h) do { _Pragma("unroll") for (int m = 0; m < 4; ++m) _Pragma("unroll") for (int k = 0; k < 2; ++k) dst[m][k] = *(const LAS bf16x8*)(lds + PG8_SA(b, h) + aoff + m * 2048 + k * 1024); } while (0)
; #define PG8_LDB(dst, b, h) do { _Pragma("unroll") for (int n = 0; n < 2; ++n) _Pragma("unroll") for (int k = 0; k < 2; ++k) dst[n][k] = *(const LAS bf16x8*)(lds + PG8_SB(b, h) + boff + n * 2048 + k * 1024); } while (0)
; #define PG8_MMA(ai, bj, At, Bt) do { __builtin_amdgcn_s_setprio(1); _Pragma("unroll") for (int m = 0; m < 4; ++m) _Pragma("unroll") for (int n = 0; n < 2; ++n) _Pragma("unroll") for (int k = 0; k < 2; ++k) \
;         acc[ai][bj][m][n] = __builtin_amdgcn_mfma_f32_16x16x32_bf16(Bt[n][k], At[m][k], acc[ai][bj][m][n], 0, 0, 0); __builtin_amdgcn_s_setprio(0); } while (0)
; #define PG8_WAIT_V(n) asm volatile("s_waitcnt vmcnt(" #n ")" ::: "memory")
; #define PG8_WAIT_L(n) asm volatile("s_waitcnt lgkmcnt(" #n ")" ::: "memory")
; #define PG8_BAR __builtin_amdgcn_s_barrier()
; #define PG8_SCHED __builtin_amdgcn_sched_barrier(0)
; template <class Epi, bool ALIGN_EPI = true, class Sched = StaticOrder>
; __device__ __forceinline__ void gemm_phase(LAS unsigned char* lds, const Gemm g, const Sched& S, const Epi& E) {
;     ...
;             PG8_WAIT_V(8); PG8_WAIT_L(0); PG8_BAR; PG8_MMA(1, 0, At, B0); PG8_MMA(1, 1, At, B1); PG8_BAR; PG8_SCHED;
;             PG8_LDB(B0, 1, 0); PG8_LDB(B1, 1, 1); PG8_SCHED; PG8_LDA(At, 1, 0); PG8_STAGE(PG8_SA(0, 1), a2 + hstepA, voffA);
;             PG8_WAIT_V(8); PG8_WAIT_L(0); PG8_BAR; PG8_MMA(0, 0, At, B0); PG8_MMA(0, 1, At, B1); PG8_BAR; PG8_SCHED;
	s_setprio 1
	s_waitcnt lgkmcnt(0)
	v_mfma_f32_16x16x32_bf16 v[62:65], v[140:143], v[180:183], v[62:65]
	v_mfma_f32_16x16x32_bf16 v[58:61], v[156:159], v[180:183], v[58:61]
	v_mfma_f32_16x16x32_bf16 v[54:57], v[140:143], v[198:201], v[54:57]
	v_mfma_f32_16x16x32_bf16 v[46:49], v[156:159], v[198:201], v[46:49]
	v_mfma_f32_16x16x32_bf16 v[38:41], v[140:143], v[216:219], v[38:41]
	v_mfma_f32_16x16x32_bf16 v[30:33], v[156:159], v[216:219], v[30:33]
	v_mfma_f32_16x16x32_bf16 v[22:25], v[140:143], v[224:227], v[22:25]
	v_mfma_f32_16x16x32_bf16 v[14:17], v[156:159], v[224:227], v[14:17]
	v_mfma_f32_16x16x32_bf16 v[62:65], v[152:155], v[184:187], v[62:65]
	v_mfma_f32_16x16x32_bf16 v[58:61], v[160:163], v[184:187], v[58:61]
	v_mfma_f32_16x16x32_bf16 v[54:57], v[152:155], v[202:205], v[54:57]
	v_mfma_f32_16x16x32_bf16 v[46:49], v[160:163], v[202:205], v[46:49]
	v_mfma_f32_16x16x32_bf16 v[38:41], v[152:155], v[220:223], v[38:41]
	v_mfma_f32_16x16x32_bf16 v[30:33], v[160:163], v[220:223], v[30:33]
	v_mfma_f32_16x16x32_bf16 v[22:25], v[152:155], v[234:237], v[22:25]
	v_mfma_f32_16x16x32_bf16 v[14:17], v[160:163], v[234:237], v[14:17]
	s_setprio 0
	s_setprio 1
	v_mfma_f32_16x16x32_bf16 v[50:53], v[164:167], v[180:183], v[50:53]
	v_mfma_f32_16x16x32_bf16 v[42:45], v[172:175], v[180:183], v[42:45]
	v_mfma_f32_16x16x32_bf16 v[34:37], v[164:167], v[198:201], v[34:37]
	v_mfma_f32_16x16x32_bf16 v[26:29], v[172:175], v[198:201], v[26:29]
	v_mfma_f32_16x16x32_bf16 v[18:21], v[164:167], v[216:219], v[18:21]
	v_mfma_f32_16x16x32_bf16 v[10:13], v[172:175], v[216:219], v[10:13]
	v_mfma_f32_16x16x32_bf16 v[6:9], v[164:167], v[224:227], v[6:9]
	v_mfma_f32_16x16x32_bf16 v[2:5], v[172:175], v[224:227], v[2:5]
	v_mfma_f32_16x16x32_bf16 v[50:53], v[168:171], v[184:187], v[50:53]
	v_mfma_f32_16x16x32_bf16 v[42:45], v[176:179], v[184:187], v[42:45]
	v_mfma_f32_16x16x32_bf16 v[34:37], v[168:171], v[202:205], v[34:37]
	v_mfma_f32_16x16x32_bf16 v[26:29], v[176:179], v[202:205], v[26:29]
	v_mfma_f32_16x16x32_bf16 v[18:21], v[168:171], v[220:223], v[18:21]
	v_mfma_f32_16x16x32_bf16 v[10:13], v[176:179], v[220:223], v[10:13]
	v_mfma_f32_16x16x32_bf16 v[6:9], v[168:171], v[234:237], v[6:9]
	v_mfma_f32_16x16x32_bf16 v[2:5], v[176:179], v[234:237], v[2:5]
	s_setprio 0
	s_barrier
	s_mov_b32 m0, s11
	s_nop 0
	global_load_lds_dwordx4 v[192:193], off
	s_mov_b32 m0, s25
	s_nop 0
	global_load_lds_dwordx4 v[194:195], off
	s_add_i32 s46, 0, 0x18000
	s_add_i32 s47, 0, 0x1c000
	v_add_u32_e32 v160, s46, v145
	v_add_u32_e32 v176, s47, v145
	ds_read_b128 v[140:143], v160
	ds_read_b128 v[152:155], v160 offset:1024
	ds_read_b128 v[156:159], v160 offset:2048
	ds_read_b128 v[160:163], v160 offset:3072
	ds_read_b128 v[164:167], v176
	ds_read_b128 v[168:171], v176 offset:1024
	ds_read_b128 v[172:175], v176 offset:2048
	ds_read_b128 v[176:179], v176 offset:3072
	s_add_u32 s36, s36, 0x40000
	s_addc_u32 s37, s37, 0
	s_mov_b32 m0, s26
	v_lshl_add_u64 v[196:197], s[36:37], 0, v[130:131]
	ds_read_b128 v[180:183], v151 offset:32768
	ds_read_b128 v[184:187], v151 offset:33792
	ds_read_b128 v[198:201], v151 offset:34816
	ds_read_b128 v[202:205], v151 offset:35840
	ds_read_b128 v[216:219], v151 offset:36864
	ds_read_b128 v[220:223], v151 offset:37888
	ds_read_b128 v[224:227], v151 offset:38912
	ds_read_b128 v[234:237], v151 offset:39936
	global_load_lds_dwordx4 v[196:197], off
	v_lshl_add_u64 v[196:197], s[36:37], 0, v[132:133]
	s_mov_b32 m0, s27
	s_nop 0
	global_load_lds_dwordx4 v[196:197], off
	s_waitcnt vmcnt(8)
	s_waitcnt lgkmcnt(0)
	s_barrier
	s_setprio 1
	s_waitcnt lgkmcnt(0)
	v_mfma_f32_16x16x32_bf16 v[126:129], v[140:143], v[180:183], v[126:129]
	v_mfma_f32_16x16x32_bf16 v[122:125], v[156:159], v[180:183], v[122:125]
	v_mfma_f32_16x16x32_bf16 v[118:121], v[140:143], v[198:201], v[118:121]
	v_mfma_f32_16x16x32_bf16 v[110:113], v[156:159], v[198:201], v[110:113]
	v_mfma_f32_16x16x32_bf16 v[102:105], v[140:143], v[216:219], v[102:105]
	v_mfma_f32_16x16x32_bf16 v[94:97], v[156:159], v[216:219], v[94:97]
	v_mfma_f32_16x16x32_bf16 v[86:89], v[140:143], v[224:227], v[86:89]
	v_mfma_f32_16x16x32_bf16 v[78:81], v[156:159], v[224:227], v[78:81]
	v_mfma_f32_16x16x32_bf16 v[126:129], v[152:155], v[184:187], v[126:129]
	v_mfma_f32_16x16x32_bf16 v[122:125], v[160:163], v[184:187], v[122:125]
	v_mfma_f32_16x16x32_bf16 v[118:121], v[152:155], v[202:205], v[118:121]
	v_mfma_f32_16x16x32_bf16 v[110:113], v[160:163], v[202:205], v[110:113]
	v_mfma_f32_16x16x32_bf16 v[102:105], v[152:155], v[220:223], v[102:105]
	v_mfma_f32_16x16x32_bf16 v[94:97], v[160:163], v[220:223], v[94:97]
	v_mfma_f32_16x16x32_bf16 v[86:89], v[152:155], v[234:237], v[86:89]
	v_mfma_f32_16x16x32_bf16 v[78:81], v[160:163], v[234:237], v[78:81]
	s_setprio 0
	s_setprio 1
	v_mfma_f32_16x16x32_bf16 v[114:117], v[164:167], v[180:183], v[114:117]
	v_mfma_f32_16x16x32_bf16 v[106:109], v[172:175], v[180:183], v[106:109]
	v_mfma_f32_16x16x32_bf16 v[98:101], v[164:167], v[198:201], v[98:101]
	v_mfma_f32_16x16x32_bf16 v[90:93], v[172:175], v[198:201], v[90:93]
	v_mfma_f32_16x16x32_bf16 v[82:85], v[164:167], v[216:219], v[82:85]
	v_mfma_f32_16x16x32_bf16 v[74:77], v[172:175], v[216:219], v[74:77]
	v_mfma_f32_16x16x32_bf16 v[70:73], v[164:167], v[224:227], v[70:73]
	v_mfma_f32_16x16x32_bf16 v[66:69], v[172:175], v[224:227], v[66:69]
	v_mfma_f32_16x16x32_bf16 v[114:117], v[168:171], v[184:187], v[114:117]
	v_mfma_f32_16x16x32_bf16 v[106:109], v[176:179], v[184:187], v[106:109]
	v_mfma_f32_16x16x32_bf16 v[98:101], v[168:171], v[202:205], v[98:101]
	v_mfma_f32_16x16x32_bf16 v[90:93], v[176:179], v[202:205], v[90:93]
	v_mfma_f32_16x16x32_bf16 v[82:85], v[168:171], v[220:223], v[82:85]
	v_mfma_f32_16x16x32_bf16 v[74:77], v[176:179], v[220:223], v[74:77]
	v_mfma_f32_16x16x32_bf16 v[70:73], v[168:171], v[234:237], v[70:73]
	v_mfma_f32_16x16x32_bf16 v[66:69], v[176:179], v[234:237], v[66:69]
	s_setprio 0
	s_barrier
; #define PG8_STAGE(bufoff, gbase, voff) do { _Pragma("unroll") for (int _i = 0; _i < 2; ++_i) \
;         __builtin_amdgcn_global_load_lds((const unsigned*)((const char*)(gbase) + (voff)[_i]), (LAS unsigned*)(lds + (bufoff) + ldsw + _i * 8192), 16, 0, 0); } while (0)
; #define PG8_LDA(dst, b, h) do { _Pragma("unroll") for (int m = 0; m < 4; ++m) _Pragma("unroll") for (int k = 0; k < 2; ++k) dst[m][k] = *(const LAS bf16x8*)(lds + PG8_SA(b, h) + aoff + m * 2048 + k * 1024); } while (0)
; #define PG8_MMA(ai, bj, At, Bt) do { __builtin_amdgcn_s_setprio(1); _Pragma("unroll") for (int m = 0; m < 4; ++m) _Pragma("unroll") for (int n = 0; n < 2; ++n) _Pragma("unroll") for (int k = 0; k < 2; ++k) \
;         acc[ai][bj][m][n] = __builtin_amdgcn_mfma_f32_16x16x32_bf16(Bt[n][k], At[m][k], acc[ai][bj][m][n], 0, 0, 0); __builtin_amdgcn_s_setprio(0); } while (0)
; #define PG8_WAIT_V(n) asm volatile("s_waitcnt vmcnt(" #n ")" ::: "memory")
; #define PG8_WAIT_L(n) asm volatile("s_waitcnt lgkmcnt(" #n ")" ::: "memory")
; #define PG8_BAR __builtin_amdgcn_s_barrier()
; #define PG8_SCHED __builtin_amdgcn_sched_barrier(0)
; template <class Epi, bool ALIGN_EPI = true, class Sched = StaticOrder>
; __device__ __forceinline__ void gemm_phase(LAS unsigned char* lds, const Gemm g, const Sched& S, const Epi& E) {
;     ...
;             PG8_LDA(At, 1, 1); PG8_STAGE(PG8_SB(1, 0), b3, voffB); PG8_STAGE(PG8_SB(1, 1), b3 + hstepB, voffB); PG8_STAGE(PG8_SA(1, 0), a3, voffA);
;             PG8_WAIT_V(8); PG8_WAIT_L(0); PG8_BAR; PG8_MMA(1, 0, At, B0); PG8_MMA(1, 1, At, B1); PG8_BAR; PG8_SCHED;
;         }
;         if constexpr (Epi::HAS_PRE) { if (has_next) E.pre(nxt, (ui + 1) & 1); }
;     __device__ __forceinline__ void pre(const Unit& u, int buf) const {
;         int t = threadIdx.x; asm volatile("" : "+v"(t));
;         if (t < 256) { const f32x4* sp = (const f32x4*)(ssp + (size_t)(u.pm * BM + t) * 16);
;             const f32x4 s4 = (sp[0] + sp[1]) + (sp[2] + sp[3]);
;             stash[buf * 256 + t] = __builtin_amdgcn_rsqf(((s4[0] + s4[1]) + (s4[2] + s4[3])) * (1.f / 1024.f) + EPS); }
;     }
	s_add_i32 s36, s46, s19
	v_lshl_add_u64 v[188:189], v[188:189], 0, s[70:71]
	s_mov_b32 m0, s36
	ds_read_b128 v[180:183], v151 offset:49152
	ds_read_b128 v[184:187], v151 offset:50176
	ds_read_b128 v[198:201], v151 offset:51200
	ds_read_b128 v[202:205], v151 offset:52224
	ds_read_b128 v[216:219], v151 offset:53248
	ds_read_b128 v[220:223], v151 offset:54272
	ds_read_b128 v[224:227], v151 offset:55296
	ds_read_b128 v[234:237], v151 offset:56320
	global_load_lds_dwordx4 v[188:189], off
	s_add_i32 m0, s36, 0x2000
	s_add_u32 s36, s60, 0x40080
	v_lshl_add_u64 v[188:189], v[190:191], 0, s[70:71]
	s_addc_u32 s37, s61, 0
	s_add_i32 s46, s47, s19
	global_load_lds_dwordx4 v[188:189], off
	v_lshl_add_u64 v[188:189], s[36:37], 0, v[0:1]
	s_mov_b32 m0, s46
	s_nop 0
	global_load_lds_dwordx4 v[188:189], off
	v_lshl_add_u64 v[188:189], s[36:37], 0, v[134:135]
	s_add_i32 m0, s46, 0x2000
	s_nop 0
	global_load_lds_dwordx4 v[188:189], off
	s_waitcnt vmcnt(6)
	s_waitcnt lgkmcnt(0)
	s_barrier
	s_setprio 1
	s_waitcnt lgkmcnt(0)
	v_mfma_f32_16x16x32_bf16 v[62:65], v[140:143], v[180:183], v[62:65]
	v_mfma_f32_16x16x32_bf16 v[58:61], v[156:159], v[180:183], v[58:61]
	v_mfma_f32_16x16x32_bf16 v[54:57], v[140:143], v[198:201], v[54:57]
	v_mfma_f32_16x16x32_bf16 v[46:49], v[156:159], v[198:201], v[46:49]
	v_mfma_f32_16x16x32_bf16 v[38:41], v[140:143], v[216:219], v[38:41]
	v_mfma_f32_16x16x32_bf16 v[30:33], v[156:159], v[216:219], v[30:33]
	v_mfma_f32_16x16x32_bf16 v[22:25], v[140:143], v[224:227], v[22:25]
	v_mfma_f32_16x16x32_bf16 v[14:17], v[156:159], v[224:227], v[14:17]
	v_mfma_f32_16x16x32_bf16 v[62:65], v[152:155], v[184:187], v[62:65]
	v_mfma_f32_16x16x32_bf16 v[58:61], v[160:163], v[184:187], v[58:61]
	v_mfma_f32_16x16x32_bf16 v[54:57], v[152:155], v[202:205], v[54:57]
	v_mfma_f32_16x16x32_bf16 v[46:49], v[160:163], v[202:205], v[46:49]
	v_mfma_f32_16x16x32_bf16 v[38:41], v[152:155], v[220:223], v[38:41]
	v_mfma_f32_16x16x32_bf16 v[30:33], v[160:163], v[220:223], v[30:33]
	v_mfma_f32_16x16x32_bf16 v[22:25], v[152:155], v[234:237], v[22:25]
	v_mfma_f32_16x16x32_bf16 v[14:17], v[160:163], v[234:237], v[14:17]
	s_setprio 0
	s_setprio 1
	v_mfma_f32_16x16x32_bf16 v[50:53], v[164:167], v[180:183], v[50:53]
	v_mfma_f32_16x16x32_bf16 v[42:45], v[172:175], v[180:183], v[42:45]
	v_mfma_f32_16x16x32_bf16 v[34:37], v[164:167], v[198:201], v[34:37]
	v_mfma_f32_16x16x32_bf16 v[26:29], v[172:175], v[198:201], v[26:29]
	v_mfma_f32_16x16x32_bf16 v[18:21], v[164:167], v[216:219], v[18:21]
	v_mfma_f32_16x16x32_bf16 v[10:13], v[172:175], v[216:219], v[10:13]
	v_mfma_f32_16x16x32_bf16 v[6:9], v[164:167], v[224:227], v[6:9]
	v_mfma_f32_16x16x32_bf16 v[2:5], v[172:175], v[224:227], v[2:5]
	v_mfma_f32_16x16x32_bf16 v[50:53], v[168:171], v[184:187], v[50:53]
	v_mfma_f32_16x16x32_bf16 v[42:45], v[176:179], v[184:187], v[42:45]
	v_mfma_f32_16x16x32_bf16 v[34:37], v[168:171], v[202:205], v[34:37]
	v_mfma_f32_16x16x32_bf16 v[26:29], v[176:179], v[202:205], v[26:29]
	v_mfma_f32_16x16x32_bf16 v[18:21], v[168:171], v[220:223], v[18:21]
	v_mfma_f32_16x16x32_bf16 v[10:13], v[176:179], v[220:223], v[10:13]
	v_mfma_f32_16x16x32_bf16 v[6:9], v[168:171], v[234:237], v[6:9]
	v_mfma_f32_16x16x32_bf16 v[2:5], v[176:179], v[234:237], v[2:5]
	s_setprio 0
	s_barrier
	s_add_i32 s45, s45, 2
	s_add_u32 s58, s58, 0x100
	s_addc_u32 s59, s59, 0
	s_add_u32 s43, s43, 0x100
	s_addc_u32 s44, s44, 0
	s_cmp_gt_u32 s45, 13
	s_cbranch_scc0 .LBB0_374
	s_and_b64 vcc, exec, s[0:1]
	s_cbranch_vccz .LBB0_379
	v_mov_b32_e32 v140, v208
	s_nop 0
	v_cmp_gt_i32_e32 vcc, s78, v140
	s_and_saveexec_b64 s[12:13], vcc
	s_cbranch_execz .LBB0_378
	v_lshl_add_u32 v142, s8, 8, v140
	v_ashrrev_i32_e32 v143, 31, v142
	v_lshlrev_b64 v[142:143], 6, v[142:143]
	v_lshl_add_u64 v[142:143], s[82:83], 0, v[142:143]
	global_load_dwordx4 v[152:155], v[142:143], off
	global_load_dwordx4 v[156:159], v[142:143], off offset:16
	global_load_dwordx4 v[160:163], v[142:143], off offset:32
	global_load_dwordx4 v[164:167], v[142:143], off offset:48
	s_lshl_b32 s7, s41, 10
	s_and_b32 s7, s7, 0x400
	s_add_i32 s7, s7, 0
	v_lshl_add_u32 v140, v140, 2, s7
	v_add_u32_e32 v140, 0x20600, v140
	s_waitcnt vmcnt(0)
	v_pk_add_f32 v[142:143], v[154:155], v[158:159]
	v_pk_add_f32 v[152:153], v[152:153], v[156:157]
	v_pk_add_f32 v[154:155], v[162:163], v[166:167]
	v_pk_add_f32 v[156:157], v[160:161], v[164:165]
	v_pk_add_f32 v[142:143], v[142:143], v[154:155]
	v_pk_add_f32 v[152:153], v[152:153], v[156:157]
	s_nop 0
	v_pk_mov_b32 v[154:155], v[152:153], v[142:143] op_sel:[1,0]
	v_mov_b32_e32 v153, v143
	v_pk_add_f32 v[142:143], v[154:155], v[152:153]
	s_nop 0
	v_add_f32_e32 v141, v142, v143
	v_fmamk_f32 v141, v141, 0x3a800000, v209
	v_rsq_f32_e32 v141, v141
	ds_write_b32 v140, v141

; __global__ void __launch_bounds__(512, 2) hybrid_fwd(Args args) {
	.amdhsa_kernel _Z10hybrid_fwd4Args
		.amdhsa_group_segment_fixed_size 0
		.amdhsa_private_segment_fixed_size 0
		.amdhsa_kernarg_size 400
		.amdhsa_user_sgpr_count 2
		.amdhsa_user_sgpr_dispatch_ptr 0
		.amdhsa_user_sgpr_queue_ptr 0
		.amdhsa_user_sgpr_kernarg_segment_ptr 1
		.amdhsa_user_sgpr_dispatch_id 0
		.amdhsa_user_sgpr_kernarg_preload_length 0
		.amdhsa_user_sgpr_kernarg_preload_offset 0
		.amdhsa_user_sgpr_private_segment_size 0
		.amdhsa_uses_dynamic_stack 0
		.amdhsa_enable_private_segment 0
		.amdhsa_system_sgpr_workgroup_id_x 1
		.amdhsa_system_sgpr_workgroup_id_y 0
		.amdhsa_system_sgpr_workgroup_id_z 0
		.amdhsa_system_sgpr_workgroup_info 0
		.amdhsa_system_vgpr_workitem_id 2
		.amdhsa_next_free_vgpr 255
		.amdhsa_next_free_sgpr 102
		.amdhsa_accum_offset 256
		.amdhsa_reserve_vcc 1
		.amdhsa_float_round_mode_32 0
		.amdhsa_float_round_mode_16_64 0
		.amdhsa_float_denorm_mode_32 3
		.amdhsa_float_denorm_mode_16_64 3
		.amdhsa_dx10_clamp 1
		.amdhsa_ieee_mode 1
		.amdhsa_fp16_overflow 0
		.amdhsa_tg_split 0
		.amdhsa_exception_fp_ieee_invalid_op 0
		.amdhsa_exception_fp_denorm_src 0
		.amdhsa_exception_fp_ieee_div_zero 0
		.amdhsa_exception_fp_ieee_overflow 0
		.amdhsa_exception_fp_ieee_underflow 0
		.amdhsa_exception_fp_ieee_inexact 0
		.amdhsa_exception_int_div_zero 0
	.end_amdhsa_kernel

; __global__ void __launch_bounds__(512, 2) hybrid_fwd(Args args) {
amdhsa.kernels:
  - .agpr_count:     0
    .args:
      - .offset:         0
        .size:           144
        .value_kind:     by_value
      - .offset:         144
        .size:           4
        .value_kind:     hidden_block_count_x
      - .offset:         148
        .size:           4
        .value_kind:     hidden_block_count_y
      - .offset:         152
        .size:           4
        .value_kind:     hidden_block_count_z
      - .offset:         156
        .size:           2
        .value_kind:     hidden_group_size_x
      - .offset:         158
        .size:           2
        .value_kind:     hidden_group_size_y
      - .offset:         160
        .size:           2
        .value_kind:     hidden_group_size_z
      - .offset:         162
        .size:           2
        .value_kind:     hidden_remainder_x
      - .offset:         164
        .size:           2
        .value_kind:     hidden_remainder_y
      - .offset:         166
        .size:           2
        .value_kind:     hidden_remainder_z
      - .offset:         184
        .size:           8
        .value_kind:     hidden_global_offset_x
      - .offset:         192
        .size:           8
        .value_kind:     hidden_global_offset_y
      - .offset:         200
        .size:           8
        .value_kind:     hidden_global_offset_z
      - .offset:         208
        .size:           2
        .value_kind:     hidden_grid_dims
      - .offset:         232
        .size:           8
        .value_kind:     hidden_multigrid_sync_arg
      - .offset:         264
        .size:           4
        .value_kind:     hidden_dynamic_lds_size
    .group_segment_fixed_size: 0
    .kernarg_segment_align: 8
    .kernarg_segment_size: 400
    .language:       OpenCL C
    .language_version:
      - 2
      - 0
    .max_flat_workgroup_size: 512
    .name:           _Z10hybrid_fwd4Args
    .private_segment_fixed_size: 0
    .sgpr_count:     108
    .sgpr_spill_count: 145
    .symbol:         _Z10hybrid_fwd4Args.kd
    .uniform_work_group_size: 1
    .uses_dynamic_stack: false
    .vgpr_count:     255
    .vgpr_spill_count: 0
    .wavefront_size: 64
